# v105 + grid barrier: followers spin on the top-level generation word; leader no longer bumps the per-XCD generation word
# speedup vs baseline: 1.0021x; 1.0021x over previous
.LBB0_1533:
	s_or_b64 exec, exec, s[2:3]
	s_mov_b64 s[2:3], exec
	v_mbcnt_lo_u32_b32 v0, s2, 0
	v_mbcnt_hi_u32_b32 v0, s3, v0
	v_cmp_eq_u32_e32 vcc, 0, v0
	s_waitcnt vmcnt(0)
	buffer_inv sc1
	s_and_saveexec_b64 s[4:5], vcc
	s_cbranch_execz .LBB0_1535
	s_bcnt1_i32_b64 s2, s[2:3]
	v_mov_b32_e32 v0, s2
	v_readlane_b32 s2, v251, 22
	v_readlane_b32 s3, v251, 23
	s_nop 4
	s_nop 0
